# s_setprio flips removed from the four GEMM K-loops
# speedup vs baseline: 1.0047x; 1.0047x over previous
.LBB0_290:
	s_add_i32 s29, s30, 2
	s_add_u32 s31, s56, 0x80
	s_addc_u32 s35, s57, 0
	s_add_i32 s72, 0, 0x10000
	s_cmp_eq_u32 s67, s30
	s_cselect_b32 s55, s1, s35
	s_cselect_b32 s54, s0, s31
	v_add_u32_e32 v144, s72, v147
	s_cselect_b32 s31, s53, s19
	s_cselect_b32 s30, s52, s18
	s_add_i32 s35, 0, 0x14000
	ds_read_b128 v[140:143], v144
	ds_read_b128 v[176:179], v144 offset:1024
	ds_read_b128 v[180:183], v144 offset:2048
	ds_read_b128 v[184:187], v144 offset:3072
	v_add_u32_e32 v144, s35, v147
	ds_read_b128 v[188:191], v144
	ds_read_b128 v[192:195], v144 offset:1024
	ds_read_b128 v[196:199], v144 offset:2048
	ds_read_b128 v[200:203], v144 offset:3072
	v_lshl_add_u64 v[144:145], s[56:57], 0, v[136:137]
	s_add_i32 m0, s58, 0xc000
	ds_read_b128 v[204:207], v169
	ds_read_b128 v[208:211], v169 offset:1024
	ds_read_b128 v[212:215], v169 offset:2048
	ds_read_b128 v[216:219], v169 offset:3072
	ds_read_b128 v[220:223], v169 offset:4096
	ds_read_b128 v[224:227], v169 offset:5120
	ds_read_b128 v[228:231], v169 offset:6144
	ds_read_b128 v[232:235], v169 offset:7168
	global_load_lds_dwordx4 v[144:145], off
	v_lshl_add_u64 v[144:145], s[56:57], 0, v[138:139]
	s_add_i32 m0, s58, 0xe000
	s_nop 0
	global_load_lds_dwordx4 v[144:145], off
	s_waitcnt vmcnt(8)
	s_waitcnt lgkmcnt(0)
	s_barrier
	s_waitcnt lgkmcnt(0)
	v_mfma_f32_16x16x32_bf16 v[126:129], v[140:143], v[204:207], v[126:129]
	v_mfma_f32_16x16x32_bf16 v[114:117], v[180:183], v[204:207], v[114:117]
	v_mfma_f32_16x16x32_bf16 v[106:109], v[140:143], v[212:215], v[106:109]
	v_mfma_f32_16x16x32_bf16 v[98:101], v[180:183], v[212:215], v[98:101]
	v_mfma_f32_16x16x32_bf16 v[90:93], v[140:143], v[220:223], v[90:93]
	v_mfma_f32_16x16x32_bf16 v[82:85], v[180:183], v[220:223], v[82:85]
	v_mfma_f32_16x16x32_bf16 v[74:77], v[140:143], v[228:231], v[74:77]
	v_mfma_f32_16x16x32_bf16 v[54:57], v[180:183], v[228:231], v[54:57]
	v_mfma_f32_16x16x32_bf16 v[126:129], v[176:179], v[208:211], v[126:129]
	v_mfma_f32_16x16x32_bf16 v[114:117], v[184:187], v[208:211], v[114:117]
	v_mfma_f32_16x16x32_bf16 v[106:109], v[176:179], v[216:219], v[106:109]
	v_mfma_f32_16x16x32_bf16 v[98:101], v[184:187], v[216:219], v[98:101]
	v_mfma_f32_16x16x32_bf16 v[90:93], v[176:179], v[224:227], v[90:93]
	v_mfma_f32_16x16x32_bf16 v[82:85], v[184:187], v[224:227], v[82:85]
	v_mfma_f32_16x16x32_bf16 v[74:77], v[176:179], v[232:235], v[74:77]
	v_mfma_f32_16x16x32_bf16 v[54:57], v[184:187], v[232:235], v[54:57]
	v_mfma_f32_16x16x32_bf16 v[118:121], v[188:191], v[204:207], v[118:121]
	v_mfma_f32_16x16x32_bf16 v[122:125], v[196:199], v[204:207], v[122:125]
	v_mfma_f32_16x16x32_bf16 v[102:105], v[188:191], v[212:215], v[102:105]
	v_mfma_f32_16x16x32_bf16 v[110:113], v[196:199], v[212:215], v[110:113]
	v_mfma_f32_16x16x32_bf16 v[86:89], v[188:191], v[220:223], v[86:89]
	v_mfma_f32_16x16x32_bf16 v[94:97], v[196:199], v[220:223], v[94:97]
	v_mfma_f32_16x16x32_bf16 v[70:73], v[188:191], v[228:231], v[70:73]
	v_mfma_f32_16x16x32_bf16 v[78:81], v[196:199], v[228:231], v[78:81]
	v_mfma_f32_16x16x32_bf16 v[118:121], v[192:195], v[208:211], v[118:121]
	v_mfma_f32_16x16x32_bf16 v[122:125], v[200:203], v[208:211], v[122:125]
	v_mfma_f32_16x16x32_bf16 v[102:105], v[192:195], v[216:219], v[102:105]
	v_mfma_f32_16x16x32_bf16 v[110:113], v[200:203], v[216:219], v[110:113]
	v_mfma_f32_16x16x32_bf16 v[86:89], v[192:195], v[224:227], v[86:89]
	v_mfma_f32_16x16x32_bf16 v[94:97], v[200:203], v[224:227], v[94:97]
	v_mfma_f32_16x16x32_bf16 v[70:73], v[192:195], v[232:235], v[70:73]
	v_mfma_f32_16x16x32_bf16 v[78:81], v[200:203], v[232:235], v[78:81]
	s_barrier
	s_add_i32 s72, s72, s23
	v_lshl_add_u64 v[144:145], s[30:31], 0, v[0:1]
	s_mov_b32 m0, s72
	ds_read_b128 v[204:207], v169 offset:16384
	ds_read_b128 v[208:211], v169 offset:17408
	ds_read_b128 v[212:215], v169 offset:18432
	ds_read_b128 v[216:219], v169 offset:19456
	ds_read_b128 v[220:223], v169 offset:20480
	ds_read_b128 v[224:227], v169 offset:21504
	ds_read_b128 v[228:231], v169 offset:22528
	ds_read_b128 v[232:235], v169 offset:23552
	global_load_lds_dwordx4 v[144:145], off
	s_add_i32 m0, s72, 0x2000
	v_lshl_add_u64 v[236:237], s[30:31], 0, v[134:135]
	s_add_u32 s30, s30, s80
	s_addc_u32 s31, s31, 0
	s_add_i32 s35, s35, s23
	global_load_lds_dwordx4 v[236:237], off
	v_lshl_add_u64 v[238:239], s[30:31], 0, v[0:1]
	s_mov_b32 m0, s35
	v_lshl_add_u64 v[240:241], s[30:31], 0, v[134:135]
	global_load_lds_dwordx4 v[238:239], off
	s_add_i32 m0, s35, 0x2000
	v_lshl_add_u64 v[242:243], s[54:55], 0, v[130:131]
	global_load_lds_dwordx4 v[240:241], off
	s_mov_b32 m0, s58
	v_lshl_add_u64 v[244:245], s[54:55], 0, v[132:133]
	global_load_lds_dwordx4 v[242:243], off
	s_mov_b32 m0, s59
	s_nop 0
	global_load_lds_dwordx4 v[244:245], off
	s_waitcnt vmcnt(8)
	s_waitcnt lgkmcnt(0)
	s_barrier
	s_waitcnt lgkmcnt(0)
	v_mfma_f32_16x16x32_bf16 v[58:61], v[140:143], v[204:207], v[58:61]
	v_mfma_f32_16x16x32_bf16 v[62:65], v[180:183], v[204:207], v[62:65]
	v_mfma_f32_16x16x32_bf16 v[38:41], v[140:143], v[212:215], v[38:41]
	v_mfma_f32_16x16x32_bf16 v[42:45], v[180:183], v[212:215], v[42:45]
	v_mfma_f32_16x16x32_bf16 v[18:21], v[140:143], v[220:223], v[18:21]
	v_mfma_f32_16x16x32_bf16 v[26:29], v[180:183], v[220:223], v[26:29]
	v_mfma_f32_16x16x32_bf16 v[2:5], v[140:143], v[228:231], v[2:5]
	v_mfma_f32_16x16x32_bf16 v[6:9], v[180:183], v[228:231], v[6:9]
	v_mfma_f32_16x16x32_bf16 v[58:61], v[176:179], v[208:211], v[58:61]
	v_mfma_f32_16x16x32_bf16 v[62:65], v[184:187], v[208:211], v[62:65]
	v_mfma_f32_16x16x32_bf16 v[38:41], v[176:179], v[216:219], v[38:41]
	v_mfma_f32_16x16x32_bf16 v[42:45], v[184:187], v[216:219], v[42:45]
	v_mfma_f32_16x16x32_bf16 v[18:21], v[176:179], v[224:227], v[18:21]
	v_mfma_f32_16x16x32_bf16 v[26:29], v[184:187], v[224:227], v[26:29]
	v_mfma_f32_16x16x32_bf16 v[2:5], v[176:179], v[232:235], v[2:5]
	v_mfma_f32_16x16x32_bf16 v[6:9], v[184:187], v[232:235], v[6:9]
	v_mfma_f32_16x16x32_bf16 v[50:53], v[188:191], v[204:207], v[50:53]
	v_mfma_f32_16x16x32_bf16 v[66:69], v[196:199], v[204:207], v[66:69]
	v_mfma_f32_16x16x32_bf16 v[34:37], v[188:191], v[212:215], v[34:37]
	v_mfma_f32_16x16x32_bf16 v[46:49], v[196:199], v[212:215], v[46:49]
	v_mfma_f32_16x16x32_bf16 v[14:17], v[188:191], v[220:223], v[14:17]
	v_mfma_f32_16x16x32_bf16 v[30:33], v[196:199], v[220:223], v[30:33]
	v_mfma_f32_16x16x32_bf16 v[10:13], v[188:191], v[228:231], v[10:13]
	v_mfma_f32_16x16x32_bf16 v[22:25], v[196:199], v[228:231], v[22:25]
	v_mfma_f32_16x16x32_bf16 v[50:53], v[192:195], v[208:211], v[50:53]
	v_mfma_f32_16x16x32_bf16 v[66:69], v[200:203], v[208:211], v[66:69]
	v_mfma_f32_16x16x32_bf16 v[34:37], v[192:195], v[216:219], v[34:37]
	v_mfma_f32_16x16x32_bf16 v[46:49], v[200:203], v[216:219], v[46:49]
	v_mfma_f32_16x16x32_bf16 v[14:17], v[192:195], v[224:227], v[14:17]
	v_mfma_f32_16x16x32_bf16 v[30:33], v[200:203], v[224:227], v[30:33]
	v_mfma_f32_16x16x32_bf16 v[10:13], v[192:195], v[232:235], v[10:13]
	v_mfma_f32_16x16x32_bf16 v[22:25], v[200:203], v[232:235], v[22:25]
	s_barrier
	s_add_i32 s35, 0, 0x18000
	s_add_i32 s72, 0, 0x1c000
	v_add_u32_e32 v184, s35, v147
	v_add_u32_e32 v200, s72, v147
	ds_read_b128 v[140:143], v184
	ds_read_b128 v[176:179], v184 offset:1024
	ds_read_b128 v[180:183], v184 offset:2048
	ds_read_b128 v[184:187], v184 offset:3072
	ds_read_b128 v[188:191], v200
	ds_read_b128 v[192:195], v200 offset:1024
	ds_read_b128 v[196:199], v200 offset:2048
	ds_read_b128 v[200:203], v200 offset:3072
	s_add_u32 s30, s54, s80
	s_addc_u32 s31, s55, 0
	s_mov_b32 m0, s60
	v_lshl_add_u64 v[246:247], s[30:31], 0, v[130:131]
	ds_read_b128 v[204:207], v169 offset:32768
	ds_read_b128 v[208:211], v169 offset:33792
	ds_read_b128 v[212:215], v169 offset:34816
	ds_read_b128 v[216:219], v169 offset:35840
	ds_read_b128 v[220:223], v169 offset:36864
	ds_read_b128 v[224:227], v169 offset:37888
	ds_read_b128 v[228:231], v169 offset:38912
	ds_read_b128 v[232:235], v169 offset:39936
	global_load_lds_dwordx4 v[246:247], off
	v_lshl_add_u64 v[246:247], s[30:31], 0, v[132:133]
	s_mov_b32 m0, s61
	s_nop 0
	global_load_lds_dwordx4 v[246:247], off
	s_waitcnt vmcnt(8)
	s_waitcnt lgkmcnt(0)
	s_barrier
	s_waitcnt lgkmcnt(0)
	v_mfma_f32_16x16x32_bf16 v[126:129], v[140:143], v[204:207], v[126:129]
	v_mfma_f32_16x16x32_bf16 v[114:117], v[180:183], v[204:207], v[114:117]
	v_mfma_f32_16x16x32_bf16 v[106:109], v[140:143], v[212:215], v[106:109]
	v_mfma_f32_16x16x32_bf16 v[98:101], v[180:183], v[212:215], v[98:101]
	v_mfma_f32_16x16x32_bf16 v[90:93], v[140:143], v[220:223], v[90:93]
	v_mfma_f32_16x16x32_bf16 v[82:85], v[180:183], v[220:223], v[82:85]
	v_mfma_f32_16x16x32_bf16 v[74:77], v[140:143], v[228:231], v[74:77]
	v_mfma_f32_16x16x32_bf16 v[54:57], v[180:183], v[228:231], v[54:57]
	v_mfma_f32_16x16x32_bf16 v[126:129], v[176:179], v[208:211], v[126:129]
	v_mfma_f32_16x16x32_bf16 v[114:117], v[184:187], v[208:211], v[114:117]
	v_mfma_f32_16x16x32_bf16 v[106:109], v[176:179], v[216:219], v[106:109]
	v_mfma_f32_16x16x32_bf16 v[98:101], v[184:187], v[216:219], v[98:101]
	v_mfma_f32_16x16x32_bf16 v[90:93], v[176:179], v[224:227], v[90:93]
	v_mfma_f32_16x16x32_bf16 v[82:85], v[184:187], v[224:227], v[82:85]
	v_mfma_f32_16x16x32_bf16 v[74:77], v[176:179], v[232:235], v[74:77]
	v_mfma_f32_16x16x32_bf16 v[54:57], v[184:187], v[232:235], v[54:57]
	v_mfma_f32_16x16x32_bf16 v[118:121], v[188:191], v[204:207], v[118:121]
	v_mfma_f32_16x16x32_bf16 v[122:125], v[196:199], v[204:207], v[122:125]
	v_mfma_f32_16x16x32_bf16 v[102:105], v[188:191], v[212:215], v[102:105]
	v_mfma_f32_16x16x32_bf16 v[110:113], v[196:199], v[212:215], v[110:113]
	v_mfma_f32_16x16x32_bf16 v[86:89], v[188:191], v[220:223], v[86:89]
	v_mfma_f32_16x16x32_bf16 v[94:97], v[196:199], v[220:223], v[94:97]
	v_mfma_f32_16x16x32_bf16 v[70:73], v[188:191], v[228:231], v[70:73]
	v_mfma_f32_16x16x32_bf16 v[78:81], v[196:199], v[228:231], v[78:81]
	v_mfma_f32_16x16x32_bf16 v[118:121], v[192:195], v[208:211], v[118:121]
	v_mfma_f32_16x16x32_bf16 v[122:125], v[200:203], v[208:211], v[122:125]
	v_mfma_f32_16x16x32_bf16 v[102:105], v[192:195], v[216:219], v[102:105]
	v_mfma_f32_16x16x32_bf16 v[110:113], v[200:203], v[216:219], v[110:113]
	v_mfma_f32_16x16x32_bf16 v[86:89], v[192:195], v[224:227], v[86:89]
	v_mfma_f32_16x16x32_bf16 v[94:97], v[200:203], v[224:227], v[94:97]
	v_mfma_f32_16x16x32_bf16 v[70:73], v[192:195], v[232:235], v[70:73]
	v_mfma_f32_16x16x32_bf16 v[78:81], v[200:203], v[232:235], v[78:81]
	s_barrier
	s_add_i32 s30, s35, s23
	v_lshl_add_u64 v[144:145], v[144:145], 0, s[94:95]
	s_mov_b32 m0, s30
	ds_read_b128 v[204:207], v169 offset:49152
	ds_read_b128 v[208:211], v169 offset:50176
	ds_read_b128 v[212:215], v169 offset:51200
	ds_read_b128 v[216:219], v169 offset:52224
	ds_read_b128 v[220:223], v169 offset:53248
	ds_read_b128 v[224:227], v169 offset:54272
	ds_read_b128 v[228:231], v169 offset:55296
	ds_read_b128 v[232:235], v169 offset:56320
	global_load_lds_dwordx4 v[144:145], off
	v_lshl_add_u64 v[144:145], v[236:237], 0, s[94:95]
	s_add_i32 m0, s30, 0x2000
	s_add_i32 s30, s72, s23
	global_load_lds_dwordx4 v[144:145], off
	v_lshl_add_u64 v[144:145], v[238:239], 0, s[94:95]
	s_mov_b32 m0, s30
	s_nop 0
	global_load_lds_dwordx4 v[144:145], off
	v_lshl_add_u64 v[144:145], v[240:241], 0, s[94:95]
	s_add_i32 m0, s30, 0x2000
	s_nop 0
	global_load_lds_dwordx4 v[144:145], off
	v_lshl_add_u64 v[144:145], v[242:243], 0, s[94:95]
	s_mov_b32 m0, s64
	s_nop 0
	global_load_lds_dwordx4 v[144:145], off
	v_lshl_add_u64 v[144:145], v[244:245], 0, s[94:95]
	s_mov_b32 m0, s65
	s_nop 0
	global_load_lds_dwordx4 v[144:145], off
	s_waitcnt vmcnt(8)
	s_waitcnt lgkmcnt(0)
	s_barrier
	s_waitcnt lgkmcnt(0)
	v_mfma_f32_16x16x32_bf16 v[58:61], v[140:143], v[204:207], v[58:61]
	v_mfma_f32_16x16x32_bf16 v[62:65], v[180:183], v[204:207], v[62:65]
	v_mfma_f32_16x16x32_bf16 v[38:41], v[140:143], v[212:215], v[38:41]
	v_mfma_f32_16x16x32_bf16 v[42:45], v[180:183], v[212:215], v[42:45]
	v_mfma_f32_16x16x32_bf16 v[18:21], v[140:143], v[220:223], v[18:21]
	v_mfma_f32_16x16x32_bf16 v[26:29], v[180:183], v[220:223], v[26:29]
	v_mfma_f32_16x16x32_bf16 v[2:5], v[140:143], v[228:231], v[2:5]
	v_mfma_f32_16x16x32_bf16 v[6:9], v[180:183], v[228:231], v[6:9]
	v_mfma_f32_16x16x32_bf16 v[58:61], v[176:179], v[208:211], v[58:61]
	v_mfma_f32_16x16x32_bf16 v[62:65], v[184:187], v[208:211], v[62:65]
	v_mfma_f32_16x16x32_bf16 v[38:41], v[176:179], v[216:219], v[38:41]
	v_mfma_f32_16x16x32_bf16 v[42:45], v[184:187], v[216:219], v[42:45]
	v_mfma_f32_16x16x32_bf16 v[18:21], v[176:179], v[224:227], v[18:21]
	v_mfma_f32_16x16x32_bf16 v[26:29], v[184:187], v[224:227], v[26:29]
	v_mfma_f32_16x16x32_bf16 v[2:5], v[176:179], v[232:235], v[2:5]
	v_mfma_f32_16x16x32_bf16 v[6:9], v[184:187], v[232:235], v[6:9]
	v_mfma_f32_16x16x32_bf16 v[50:53], v[188:191], v[204:207], v[50:53]
	v_mfma_f32_16x16x32_bf16 v[66:69], v[196:199], v[204:207], v[66:69]
	v_mfma_f32_16x16x32_bf16 v[34:37], v[188:191], v[212:215], v[34:37]
	v_mfma_f32_16x16x32_bf16 v[46:49], v[196:199], v[212:215], v[46:49]
	v_mfma_f32_16x16x32_bf16 v[14:17], v[188:191], v[220:223], v[14:17]
	v_mfma_f32_16x16x32_bf16 v[30:33], v[196:199], v[220:223], v[30:33]
	v_mfma_f32_16x16x32_bf16 v[10:13], v[188:191], v[228:231], v[10:13]
	v_mfma_f32_16x16x32_bf16 v[22:25], v[196:199], v[228:231], v[22:25]
	v_mfma_f32_16x16x32_bf16 v[50:53], v[192:195], v[208:211], v[50:53]
	v_mfma_f32_16x16x32_bf16 v[66:69], v[200:203], v[208:211], v[66:69]
	v_mfma_f32_16x16x32_bf16 v[34:37], v[192:195], v[216:219], v[34:37]
	v_mfma_f32_16x16x32_bf16 v[46:49], v[200:203], v[216:219], v[46:49]
	v_mfma_f32_16x16x32_bf16 v[14:17], v[192:195], v[224:227], v[14:17]
	v_mfma_f32_16x16x32_bf16 v[30:33], v[200:203], v[224:227], v[30:33]
	v_mfma_f32_16x16x32_bf16 v[10:13], v[192:195], v[232:235], v[10:13]
	v_mfma_f32_16x16x32_bf16 v[22:25], v[200:203], v[232:235], v[22:25]
	s_barrier
	s_add_u32 s56, s56, 0x100
	s_addc_u32 s57, s57, 0
	s_add_u32 s18, s18, 0x100
	s_addc_u32 s19, s19, 0
	s_cmp_ge_u32 s29, s66
	s_mov_b32 s30, s29
	s_cbranch_scc0 .LBB0_290
	s_and_b64 vcc, exec, s[20:21]
	s_cbranch_vccz .LBB0_293
	s_barrier

.LBB0_334:
	s_add_i32 s66, s20, 2
	s_add_u32 s67, s16, 0x80
	s_addc_u32 s21, s17, 0
	s_add_i32 s72, 0, 0x10000
	s_cmp_eq_u32 s58, s20
	s_cselect_b32 s21, s1, s21
	s_cselect_b32 s20, s0, s67
	v_add_u32_e32 v140, s72, v143
	s_cselect_b32 s71, s15, s65
	s_cselect_b32 s70, s14, s64
	s_add_i32 s67, 0, 0x14000
	ds_read_b128 v[160:163], v140
	ds_read_b128 v[164:167], v140 offset:1024
	ds_read_b128 v[168:171], v140 offset:2048
	ds_read_b128 v[172:175], v140 offset:3072
	v_add_u32_e32 v140, s67, v143
	ds_read_b128 v[176:179], v140
	ds_read_b128 v[180:183], v140 offset:1024
	ds_read_b128 v[184:187], v140 offset:2048
	ds_read_b128 v[188:191], v140 offset:3072
	v_lshl_add_u64 v[140:141], s[16:17], 0, v[136:137]
	s_add_i32 m0, s19, 0xc000
	ds_read_b128 v[192:195], v146
	ds_read_b128 v[196:199], v146 offset:1024
	ds_read_b128 v[200:203], v146 offset:2048
	ds_read_b128 v[204:207], v146 offset:3072
	ds_read_b128 v[208:211], v146 offset:4096
	ds_read_b128 v[212:215], v146 offset:5120
	ds_read_b128 v[216:219], v146 offset:6144
	ds_read_b128 v[220:223], v146 offset:7168
	global_load_lds_dwordx4 v[140:141], off
	v_lshl_add_u64 v[140:141], s[16:17], 0, v[138:139]
	s_add_i32 m0, s19, 0xe000
	s_nop 0
	global_load_lds_dwordx4 v[140:141], off
	s_waitcnt vmcnt(8)
	s_waitcnt lgkmcnt(0)
	s_barrier
	s_waitcnt lgkmcnt(0)
	v_mfma_f32_16x16x32_bf16 v[126:129], v[160:163], v[192:195], v[126:129]
	v_mfma_f32_16x16x32_bf16 v[122:125], v[168:171], v[192:195], v[122:125]
	v_mfma_f32_16x16x32_bf16 v[110:113], v[160:163], v[200:203], v[110:113]
	v_mfma_f32_16x16x32_bf16 v[106:109], v[168:171], v[200:203], v[106:109]
	v_mfma_f32_16x16x32_bf16 v[94:97], v[160:163], v[208:211], v[94:97]
	v_mfma_f32_16x16x32_bf16 v[90:93], v[168:171], v[208:211], v[90:93]
	v_mfma_f32_16x16x32_bf16 v[78:81], v[160:163], v[216:219], v[78:81]
	v_mfma_f32_16x16x32_bf16 v[74:77], v[168:171], v[216:219], v[74:77]
	v_mfma_f32_16x16x32_bf16 v[126:129], v[164:167], v[196:199], v[126:129]
	v_mfma_f32_16x16x32_bf16 v[122:125], v[172:175], v[196:199], v[122:125]
	v_mfma_f32_16x16x32_bf16 v[110:113], v[164:167], v[204:207], v[110:113]
	v_mfma_f32_16x16x32_bf16 v[106:109], v[172:175], v[204:207], v[106:109]
	v_mfma_f32_16x16x32_bf16 v[94:97], v[164:167], v[212:215], v[94:97]
	v_mfma_f32_16x16x32_bf16 v[90:93], v[172:175], v[212:215], v[90:93]
	v_mfma_f32_16x16x32_bf16 v[78:81], v[164:167], v[220:223], v[78:81]
	v_mfma_f32_16x16x32_bf16 v[74:77], v[172:175], v[220:223], v[74:77]
	v_mfma_f32_16x16x32_bf16 v[118:121], v[176:179], v[192:195], v[118:121]
	v_mfma_f32_16x16x32_bf16 v[114:117], v[184:187], v[192:195], v[114:117]
	v_mfma_f32_16x16x32_bf16 v[102:105], v[176:179], v[200:203], v[102:105]
	v_mfma_f32_16x16x32_bf16 v[98:101], v[184:187], v[200:203], v[98:101]
	v_mfma_f32_16x16x32_bf16 v[86:89], v[176:179], v[208:211], v[86:89]
	v_mfma_f32_16x16x32_bf16 v[82:85], v[184:187], v[208:211], v[82:85]
	v_mfma_f32_16x16x32_bf16 v[70:73], v[176:179], v[216:219], v[70:73]
	v_mfma_f32_16x16x32_bf16 v[66:69], v[184:187], v[216:219], v[66:69]
	v_mfma_f32_16x16x32_bf16 v[118:121], v[180:183], v[196:199], v[118:121]
	v_mfma_f32_16x16x32_bf16 v[114:117], v[188:191], v[196:199], v[114:117]
	v_mfma_f32_16x16x32_bf16 v[102:105], v[180:183], v[204:207], v[102:105]
	v_mfma_f32_16x16x32_bf16 v[98:101], v[188:191], v[204:207], v[98:101]
	v_mfma_f32_16x16x32_bf16 v[86:89], v[180:183], v[212:215], v[86:89]
	v_mfma_f32_16x16x32_bf16 v[82:85], v[188:191], v[212:215], v[82:85]
	v_mfma_f32_16x16x32_bf16 v[70:73], v[180:183], v[220:223], v[70:73]
	v_mfma_f32_16x16x32_bf16 v[66:69], v[188:191], v[220:223], v[66:69]
	s_barrier
	s_add_i32 s72, s72, s35
	v_lshl_add_u64 v[140:141], s[70:71], 0, v[0:1]
	s_mov_b32 m0, s72
	ds_read_b128 v[192:195], v146 offset:16384
	ds_read_b128 v[196:199], v146 offset:17408
	ds_read_b128 v[200:203], v146 offset:18432
	ds_read_b128 v[204:207], v146 offset:19456
	ds_read_b128 v[208:211], v146 offset:20480
	ds_read_b128 v[212:215], v146 offset:21504
	ds_read_b128 v[216:219], v146 offset:22528
	ds_read_b128 v[220:223], v146 offset:23552
	global_load_lds_dwordx4 v[140:141], off
	s_add_i32 m0, s72, 0x2000
	v_lshl_add_u64 v[148:149], s[70:71], 0, v[134:135]
	s_add_u32 s70, s70, s80
	s_addc_u32 s71, s71, 0
	s_add_i32 s67, s67, s35
	global_load_lds_dwordx4 v[148:149], off
	v_lshl_add_u64 v[224:225], s[70:71], 0, v[0:1]
	s_mov_b32 m0, s67
	v_lshl_add_u64 v[226:227], s[70:71], 0, v[134:135]
	global_load_lds_dwordx4 v[224:225], off
	s_add_i32 m0, s67, 0x2000
	v_lshl_add_u64 v[228:229], s[20:21], 0, v[130:131]
	global_load_lds_dwordx4 v[226:227], off
	s_mov_b32 m0, s19
	v_lshl_add_u64 v[230:231], s[20:21], 0, v[132:133]
	global_load_lds_dwordx4 v[228:229], off
	s_mov_b32 m0, s29
	s_nop 0
	global_load_lds_dwordx4 v[230:231], off
	s_waitcnt vmcnt(8)
	s_waitcnt lgkmcnt(0)
	s_barrier
	s_waitcnt lgkmcnt(0)
	v_mfma_f32_16x16x32_bf16 v[62:65], v[160:163], v[192:195], v[62:65]
	v_mfma_f32_16x16x32_bf16 v[58:61], v[168:171], v[192:195], v[58:61]
	v_mfma_f32_16x16x32_bf16 v[46:49], v[160:163], v[200:203], v[46:49]
	v_mfma_f32_16x16x32_bf16 v[42:45], v[168:171], v[200:203], v[42:45]
	v_mfma_f32_16x16x32_bf16 v[30:33], v[160:163], v[208:211], v[30:33]
	v_mfma_f32_16x16x32_bf16 v[26:29], v[168:171], v[208:211], v[26:29]
	v_mfma_f32_16x16x32_bf16 v[14:17], v[160:163], v[216:219], v[14:17]
	v_mfma_f32_16x16x32_bf16 v[10:13], v[168:171], v[216:219], v[10:13]
	v_mfma_f32_16x16x32_bf16 v[62:65], v[164:167], v[196:199], v[62:65]
	v_mfma_f32_16x16x32_bf16 v[58:61], v[172:175], v[196:199], v[58:61]
	v_mfma_f32_16x16x32_bf16 v[46:49], v[164:167], v[204:207], v[46:49]
	v_mfma_f32_16x16x32_bf16 v[42:45], v[172:175], v[204:207], v[42:45]
	v_mfma_f32_16x16x32_bf16 v[30:33], v[164:167], v[212:215], v[30:33]
	v_mfma_f32_16x16x32_bf16 v[26:29], v[172:175], v[212:215], v[26:29]
	v_mfma_f32_16x16x32_bf16 v[14:17], v[164:167], v[220:223], v[14:17]
	v_mfma_f32_16x16x32_bf16 v[10:13], v[172:175], v[220:223], v[10:13]
	v_mfma_f32_16x16x32_bf16 v[54:57], v[176:179], v[192:195], v[54:57]
	v_mfma_f32_16x16x32_bf16 v[50:53], v[184:187], v[192:195], v[50:53]
	v_mfma_f32_16x16x32_bf16 v[38:41], v[176:179], v[200:203], v[38:41]
	v_mfma_f32_16x16x32_bf16 v[34:37], v[184:187], v[200:203], v[34:37]
	v_mfma_f32_16x16x32_bf16 v[22:25], v[176:179], v[208:211], v[22:25]
	v_mfma_f32_16x16x32_bf16 v[18:21], v[184:187], v[208:211], v[18:21]
	v_mfma_f32_16x16x32_bf16 v[6:9], v[176:179], v[216:219], v[6:9]
	v_mfma_f32_16x16x32_bf16 v[2:5], v[184:187], v[216:219], v[2:5]
	v_mfma_f32_16x16x32_bf16 v[54:57], v[180:183], v[196:199], v[54:57]
	v_mfma_f32_16x16x32_bf16 v[50:53], v[188:191], v[196:199], v[50:53]
	v_mfma_f32_16x16x32_bf16 v[38:41], v[180:183], v[204:207], v[38:41]
	v_mfma_f32_16x16x32_bf16 v[34:37], v[188:191], v[204:207], v[34:37]
	v_mfma_f32_16x16x32_bf16 v[22:25], v[180:183], v[212:215], v[22:25]
	v_mfma_f32_16x16x32_bf16 v[18:21], v[188:191], v[212:215], v[18:21]
	v_mfma_f32_16x16x32_bf16 v[6:9], v[180:183], v[220:223], v[6:9]
	v_mfma_f32_16x16x32_bf16 v[2:5], v[188:191], v[220:223], v[2:5]
	s_barrier
	s_add_i32 s67, 0, 0x18000
	v_add_u32_e32 v159, s67, v143
	s_add_i32 s70, 0, 0x1c000
	ds_read_b128 v[160:163], v159
	ds_read_b128 v[164:167], v159 offset:1024
	ds_read_b128 v[168:171], v159 offset:2048
	ds_read_b128 v[172:175], v159 offset:3072
	v_add_u32_e32 v159, s70, v143
	ds_read_b128 v[176:179], v159
	ds_read_b128 v[180:183], v159 offset:1024
	ds_read_b128 v[184:187], v159 offset:2048
	ds_read_b128 v[188:191], v159 offset:3072
	s_add_u32 s20, s20, s80
	s_addc_u32 s21, s21, 0
	s_mov_b32 m0, s30
	v_lshl_add_u64 v[232:233], s[20:21], 0, v[130:131]
	ds_read_b128 v[192:195], v146 offset:32768
	ds_read_b128 v[196:199], v146 offset:33792
	ds_read_b128 v[200:203], v146 offset:34816
	ds_read_b128 v[204:207], v146 offset:35840
	ds_read_b128 v[208:211], v146 offset:36864
	ds_read_b128 v[212:215], v146 offset:37888
	ds_read_b128 v[216:219], v146 offset:38912
	ds_read_b128 v[220:223], v146 offset:39936
	global_load_lds_dwordx4 v[232:233], off
	v_lshl_add_u64 v[232:233], s[20:21], 0, v[132:133]
	s_mov_b32 m0, s31
	s_nop 0
	global_load_lds_dwordx4 v[232:233], off
	s_waitcnt vmcnt(8)
	s_waitcnt lgkmcnt(0)
	s_barrier
	s_waitcnt lgkmcnt(0)
	v_mfma_f32_16x16x32_bf16 v[126:129], v[160:163], v[192:195], v[126:129]
	v_mfma_f32_16x16x32_bf16 v[122:125], v[168:171], v[192:195], v[122:125]
	v_mfma_f32_16x16x32_bf16 v[110:113], v[160:163], v[200:203], v[110:113]
	v_mfma_f32_16x16x32_bf16 v[106:109], v[168:171], v[200:203], v[106:109]
	v_mfma_f32_16x16x32_bf16 v[94:97], v[160:163], v[208:211], v[94:97]
	v_mfma_f32_16x16x32_bf16 v[90:93], v[168:171], v[208:211], v[90:93]
	v_mfma_f32_16x16x32_bf16 v[78:81], v[160:163], v[216:219], v[78:81]
	v_mfma_f32_16x16x32_bf16 v[74:77], v[168:171], v[216:219], v[74:77]
	v_mfma_f32_16x16x32_bf16 v[126:129], v[164:167], v[196:199], v[126:129]
	v_mfma_f32_16x16x32_bf16 v[122:125], v[172:175], v[196:199], v[122:125]
	v_mfma_f32_16x16x32_bf16 v[110:113], v[164:167], v[204:207], v[110:113]
	v_mfma_f32_16x16x32_bf16 v[106:109], v[172:175], v[204:207], v[106:109]
	v_mfma_f32_16x16x32_bf16 v[94:97], v[164:167], v[212:215], v[94:97]
	v_mfma_f32_16x16x32_bf16 v[90:93], v[172:175], v[212:215], v[90:93]
	v_mfma_f32_16x16x32_bf16 v[78:81], v[164:167], v[220:223], v[78:81]
	v_mfma_f32_16x16x32_bf16 v[74:77], v[172:175], v[220:223], v[74:77]
	v_mfma_f32_16x16x32_bf16 v[118:121], v[176:179], v[192:195], v[118:121]
	v_mfma_f32_16x16x32_bf16 v[114:117], v[184:187], v[192:195], v[114:117]
	v_mfma_f32_16x16x32_bf16 v[102:105], v[176:179], v[200:203], v[102:105]
	v_mfma_f32_16x16x32_bf16 v[98:101], v[184:187], v[200:203], v[98:101]
	v_mfma_f32_16x16x32_bf16 v[86:89], v[176:179], v[208:211], v[86:89]
	v_mfma_f32_16x16x32_bf16 v[82:85], v[184:187], v[208:211], v[82:85]
	v_mfma_f32_16x16x32_bf16 v[70:73], v[176:179], v[216:219], v[70:73]
	v_mfma_f32_16x16x32_bf16 v[66:69], v[184:187], v[216:219], v[66:69]
	v_mfma_f32_16x16x32_bf16 v[118:121], v[180:183], v[196:199], v[118:121]
	v_mfma_f32_16x16x32_bf16 v[114:117], v[188:191], v[196:199], v[114:117]
	v_mfma_f32_16x16x32_bf16 v[102:105], v[180:183], v[204:207], v[102:105]
	v_mfma_f32_16x16x32_bf16 v[98:101], v[188:191], v[204:207], v[98:101]
	v_mfma_f32_16x16x32_bf16 v[86:89], v[180:183], v[212:215], v[86:89]
	v_mfma_f32_16x16x32_bf16 v[82:85], v[188:191], v[212:215], v[82:85]
	v_mfma_f32_16x16x32_bf16 v[70:73], v[180:183], v[220:223], v[70:73]
	v_mfma_f32_16x16x32_bf16 v[66:69], v[188:191], v[220:223], v[66:69]
	s_barrier
	s_add_i32 s20, s67, s35
	v_lshl_add_u64 v[140:141], v[140:141], 0, s[94:95]
	s_mov_b32 m0, s20
	ds_read_b128 v[192:195], v146 offset:49152
	ds_read_b128 v[196:199], v146 offset:50176
	ds_read_b128 v[200:203], v146 offset:51200
	ds_read_b128 v[204:207], v146 offset:52224
	ds_read_b128 v[208:211], v146 offset:53248
	ds_read_b128 v[212:215], v146 offset:54272
	ds_read_b128 v[216:219], v146 offset:55296
	ds_read_b128 v[220:223], v146 offset:56320
	global_load_lds_dwordx4 v[140:141], off
	v_lshl_add_u64 v[140:141], v[148:149], 0, s[94:95]
	s_add_i32 m0, s20, 0x2000
	s_add_i32 s20, s70, s35
	global_load_lds_dwordx4 v[140:141], off
	v_lshl_add_u64 v[140:141], v[224:225], 0, s[94:95]
	s_mov_b32 m0, s20
	s_nop 0
	global_load_lds_dwordx4 v[140:141], off
	v_lshl_add_u64 v[140:141], v[226:227], 0, s[94:95]
	s_add_i32 m0, s20, 0x2000
	s_nop 0
	global_load_lds_dwordx4 v[140:141], off
	v_lshl_add_u64 v[140:141], v[228:229], 0, s[94:95]
	s_mov_b32 m0, s56
	s_nop 0
	global_load_lds_dwordx4 v[140:141], off
	v_lshl_add_u64 v[140:141], v[230:231], 0, s[94:95]
	s_mov_b32 m0, s57
	s_nop 0
	global_load_lds_dwordx4 v[140:141], off
	s_waitcnt vmcnt(8)
	s_waitcnt lgkmcnt(0)
	s_barrier
	s_waitcnt lgkmcnt(0)
	v_mfma_f32_16x16x32_bf16 v[62:65], v[160:163], v[192:195], v[62:65]
	v_mfma_f32_16x16x32_bf16 v[58:61], v[168:171], v[192:195], v[58:61]
	v_mfma_f32_16x16x32_bf16 v[46:49], v[160:163], v[200:203], v[46:49]
	v_mfma_f32_16x16x32_bf16 v[42:45], v[168:171], v[200:203], v[42:45]
	v_mfma_f32_16x16x32_bf16 v[30:33], v[160:163], v[208:211], v[30:33]
	v_mfma_f32_16x16x32_bf16 v[26:29], v[168:171], v[208:211], v[26:29]
	v_mfma_f32_16x16x32_bf16 v[14:17], v[160:163], v[216:219], v[14:17]
	v_mfma_f32_16x16x32_bf16 v[10:13], v[168:171], v[216:219], v[10:13]
	v_mfma_f32_16x16x32_bf16 v[62:65], v[164:167], v[196:199], v[62:65]
	v_mfma_f32_16x16x32_bf16 v[58:61], v[172:175], v[196:199], v[58:61]
	v_mfma_f32_16x16x32_bf16 v[46:49], v[164:167], v[204:207], v[46:49]
	v_mfma_f32_16x16x32_bf16 v[42:45], v[172:175], v[204:207], v[42:45]
	v_mfma_f32_16x16x32_bf16 v[30:33], v[164:167], v[212:215], v[30:33]
	v_mfma_f32_16x16x32_bf16 v[26:29], v[172:175], v[212:215], v[26:29]
	v_mfma_f32_16x16x32_bf16 v[14:17], v[164:167], v[220:223], v[14:17]
	v_mfma_f32_16x16x32_bf16 v[10:13], v[172:175], v[220:223], v[10:13]
	v_mfma_f32_16x16x32_bf16 v[54:57], v[176:179], v[192:195], v[54:57]
	v_mfma_f32_16x16x32_bf16 v[50:53], v[184:187], v[192:195], v[50:53]
	v_mfma_f32_16x16x32_bf16 v[38:41], v[176:179], v[200:203], v[38:41]
	v_mfma_f32_16x16x32_bf16 v[34:37], v[184:187], v[200:203], v[34:37]
	v_mfma_f32_16x16x32_bf16 v[22:25], v[176:179], v[208:211], v[22:25]
	v_mfma_f32_16x16x32_bf16 v[18:21], v[184:187], v[208:211], v[18:21]
	v_mfma_f32_16x16x32_bf16 v[6:9], v[176:179], v[216:219], v[6:9]
	v_mfma_f32_16x16x32_bf16 v[2:5], v[184:187], v[216:219], v[2:5]
	v_mfma_f32_16x16x32_bf16 v[54:57], v[180:183], v[196:199], v[54:57]
	v_mfma_f32_16x16x32_bf16 v[50:53], v[188:191], v[196:199], v[50:53]
	v_mfma_f32_16x16x32_bf16 v[38:41], v[180:183], v[204:207], v[38:41]
	v_mfma_f32_16x16x32_bf16 v[34:37], v[188:191], v[204:207], v[34:37]
	v_mfma_f32_16x16x32_bf16 v[22:25], v[180:183], v[212:215], v[22:25]
	v_mfma_f32_16x16x32_bf16 v[18:21], v[188:191], v[212:215], v[18:21]
	v_mfma_f32_16x16x32_bf16 v[6:9], v[180:183], v[220:223], v[6:9]
	v_mfma_f32_16x16x32_bf16 v[2:5], v[188:191], v[220:223], v[2:5]
	s_barrier
	s_add_u32 s16, s16, 0x100
	s_addc_u32 s17, s17, 0
	s_add_u32 s64, s64, 0x100
	s_addc_u32 s65, s65, 0
	s_cmp_ge_u32 s66, s55
	s_mov_b32 s20, s66
	s_cbranch_scc0 .LBB0_334
	s_and_b64 vcc, exec, s[10:11]
	s_cbranch_vccz .LBB0_337
	s_barrier

.LBB0_360:
	s_add_i32 s30, s10, 2
	s_add_u32 s31, s2, 0x80
	s_addc_u32 s11, s3, 0
	s_add_i32 s35, 0, 0x10000
	s_cmp_eq_u32 s58, s10
	s_cselect_b32 s11, s1, s11
	s_cselect_b32 s10, s0, s31
	v_add_u32_e32 v148, s35, v160
	s_cselect_b32 s67, s7, s29
	s_cselect_b32 s66, s6, s19
	s_add_i32 s31, 0, 0x14000
	ds_read_b128 v[140:143], v148
	ds_read_b128 v[144:147], v148 offset:1024
	ds_read_b128 v[180:183], v148 offset:2048
	ds_read_b128 v[184:187], v148 offset:3072
	v_add_u32_e32 v148, s31, v160
	ds_read_b128 v[188:191], v148
	ds_read_b128 v[192:195], v148 offset:1024
	ds_read_b128 v[196:199], v148 offset:2048
	ds_read_b128 v[200:203], v148 offset:3072
	v_lshl_add_u64 v[148:149], s[2:3], 0, v[136:137]
	s_add_i32 m0, s23, 0xc000
	ds_read_b128 v[204:207], v172
	ds_read_b128 v[208:211], v172 offset:1024
	ds_read_b128 v[212:215], v172 offset:2048
	ds_read_b128 v[216:219], v172 offset:3072
	ds_read_b128 v[220:223], v172 offset:4096
	ds_read_b128 v[224:227], v172 offset:5120
	ds_read_b128 v[228:231], v172 offset:6144
	ds_read_b128 v[232:235], v172 offset:7168
	global_load_lds_dwordx4 v[148:149], off
	v_lshl_add_u64 v[148:149], s[2:3], 0, v[138:139]
	s_add_i32 m0, s23, 0xe000
	s_nop 0
	global_load_lds_dwordx4 v[148:149], off
	s_waitcnt vmcnt(8)
	s_waitcnt lgkmcnt(0)
	s_barrier
	s_waitcnt lgkmcnt(0)
	v_mfma_f32_16x16x32_bf16 v[126:129], v[140:143], v[204:207], v[126:129]
	v_mfma_f32_16x16x32_bf16 v[122:125], v[180:183], v[204:207], v[122:125]
	v_mfma_f32_16x16x32_bf16 v[110:113], v[140:143], v[212:215], v[110:113]
	v_mfma_f32_16x16x32_bf16 v[106:109], v[180:183], v[212:215], v[106:109]
	v_mfma_f32_16x16x32_bf16 v[94:97], v[140:143], v[220:223], v[94:97]
	v_mfma_f32_16x16x32_bf16 v[90:93], v[180:183], v[220:223], v[90:93]
	v_mfma_f32_16x16x32_bf16 v[78:81], v[140:143], v[228:231], v[78:81]
	v_mfma_f32_16x16x32_bf16 v[74:77], v[180:183], v[228:231], v[74:77]
	v_mfma_f32_16x16x32_bf16 v[126:129], v[144:147], v[208:211], v[126:129]
	v_mfma_f32_16x16x32_bf16 v[122:125], v[184:187], v[208:211], v[122:125]
	v_mfma_f32_16x16x32_bf16 v[110:113], v[144:147], v[216:219], v[110:113]
	v_mfma_f32_16x16x32_bf16 v[106:109], v[184:187], v[216:219], v[106:109]
	v_mfma_f32_16x16x32_bf16 v[94:97], v[144:147], v[224:227], v[94:97]
	v_mfma_f32_16x16x32_bf16 v[90:93], v[184:187], v[224:227], v[90:93]
	v_mfma_f32_16x16x32_bf16 v[78:81], v[144:147], v[232:235], v[78:81]
	v_mfma_f32_16x16x32_bf16 v[74:77], v[184:187], v[232:235], v[74:77]
	v_mfma_f32_16x16x32_bf16 v[118:121], v[188:191], v[204:207], v[118:121]
	v_mfma_f32_16x16x32_bf16 v[114:117], v[196:199], v[204:207], v[114:117]
	v_mfma_f32_16x16x32_bf16 v[102:105], v[188:191], v[212:215], v[102:105]
	v_mfma_f32_16x16x32_bf16 v[98:101], v[196:199], v[212:215], v[98:101]
	v_mfma_f32_16x16x32_bf16 v[86:89], v[188:191], v[220:223], v[86:89]
	v_mfma_f32_16x16x32_bf16 v[82:85], v[196:199], v[220:223], v[82:85]
	v_mfma_f32_16x16x32_bf16 v[70:73], v[188:191], v[228:231], v[70:73]
	v_mfma_f32_16x16x32_bf16 v[66:69], v[196:199], v[228:231], v[66:69]
	v_mfma_f32_16x16x32_bf16 v[118:121], v[192:195], v[208:211], v[118:121]
	v_mfma_f32_16x16x32_bf16 v[114:117], v[200:203], v[208:211], v[114:117]
	v_mfma_f32_16x16x32_bf16 v[102:105], v[192:195], v[216:219], v[102:105]
	v_mfma_f32_16x16x32_bf16 v[98:101], v[200:203], v[216:219], v[98:101]
	v_mfma_f32_16x16x32_bf16 v[86:89], v[192:195], v[224:227], v[86:89]
	v_mfma_f32_16x16x32_bf16 v[82:85], v[200:203], v[224:227], v[82:85]
	v_mfma_f32_16x16x32_bf16 v[70:73], v[192:195], v[232:235], v[70:73]
	v_mfma_f32_16x16x32_bf16 v[66:69], v[200:203], v[232:235], v[66:69]
	s_barrier
	s_add_i32 s35, s35, s20
	v_lshl_add_u64 v[148:149], s[66:67], 0, v[0:1]
	s_mov_b32 m0, s35
	ds_read_b128 v[204:207], v172 offset:16384
	ds_read_b128 v[208:211], v172 offset:17408
	ds_read_b128 v[212:215], v172 offset:18432
	ds_read_b128 v[216:219], v172 offset:19456
	ds_read_b128 v[220:223], v172 offset:20480
	ds_read_b128 v[224:227], v172 offset:21504
	ds_read_b128 v[228:231], v172 offset:22528
	ds_read_b128 v[232:235], v172 offset:23552
	global_load_lds_dwordx4 v[148:149], off
	s_add_i32 m0, s35, 0x2000
	v_lshl_add_u64 v[236:237], s[66:67], 0, v[134:135]
	s_add_u32 s66, s66, s16
	s_addc_u32 s67, s67, 0
	s_add_i32 s31, s31, s20
	global_load_lds_dwordx4 v[236:237], off
	v_lshl_add_u64 v[238:239], s[66:67], 0, v[0:1]
	s_mov_b32 m0, s31
	v_lshl_add_u64 v[240:241], s[66:67], 0, v[134:135]
	global_load_lds_dwordx4 v[238:239], off
	s_add_i32 m0, s31, 0x2000
	v_lshl_add_u64 v[242:243], s[10:11], 0, v[130:131]
	global_load_lds_dwordx4 v[240:241], off
	s_mov_b32 m0, s23
	v_lshl_add_u64 v[244:245], s[10:11], 0, v[132:133]
	global_load_lds_dwordx4 v[242:243], off
	s_mov_b32 m0, s52
	s_nop 0
	global_load_lds_dwordx4 v[244:245], off
	s_waitcnt vmcnt(8)
	s_waitcnt lgkmcnt(0)
	s_barrier
	s_waitcnt lgkmcnt(0)
	v_mfma_f32_16x16x32_bf16 v[62:65], v[140:143], v[204:207], v[62:65]
	v_mfma_f32_16x16x32_bf16 v[58:61], v[180:183], v[204:207], v[58:61]
	v_mfma_f32_16x16x32_bf16 v[46:49], v[140:143], v[212:215], v[46:49]
	v_mfma_f32_16x16x32_bf16 v[42:45], v[180:183], v[212:215], v[42:45]
	v_mfma_f32_16x16x32_bf16 v[30:33], v[140:143], v[220:223], v[30:33]
	v_mfma_f32_16x16x32_bf16 v[26:29], v[180:183], v[220:223], v[26:29]
	v_mfma_f32_16x16x32_bf16 v[14:17], v[140:143], v[228:231], v[14:17]
	v_mfma_f32_16x16x32_bf16 v[10:13], v[180:183], v[228:231], v[10:13]
	v_mfma_f32_16x16x32_bf16 v[62:65], v[144:147], v[208:211], v[62:65]
	v_mfma_f32_16x16x32_bf16 v[58:61], v[184:187], v[208:211], v[58:61]
	v_mfma_f32_16x16x32_bf16 v[46:49], v[144:147], v[216:219], v[46:49]
	v_mfma_f32_16x16x32_bf16 v[42:45], v[184:187], v[216:219], v[42:45]
	v_mfma_f32_16x16x32_bf16 v[30:33], v[144:147], v[224:227], v[30:33]
	v_mfma_f32_16x16x32_bf16 v[26:29], v[184:187], v[224:227], v[26:29]
	v_mfma_f32_16x16x32_bf16 v[14:17], v[144:147], v[232:235], v[14:17]
	v_mfma_f32_16x16x32_bf16 v[10:13], v[184:187], v[232:235], v[10:13]
	v_mfma_f32_16x16x32_bf16 v[54:57], v[188:191], v[204:207], v[54:57]
	v_mfma_f32_16x16x32_bf16 v[50:53], v[196:199], v[204:207], v[50:53]
	v_mfma_f32_16x16x32_bf16 v[38:41], v[188:191], v[212:215], v[38:41]
	v_mfma_f32_16x16x32_bf16 v[34:37], v[196:199], v[212:215], v[34:37]
	v_mfma_f32_16x16x32_bf16 v[22:25], v[188:191], v[220:223], v[22:25]
	v_mfma_f32_16x16x32_bf16 v[18:21], v[196:199], v[220:223], v[18:21]
	v_mfma_f32_16x16x32_bf16 v[6:9], v[188:191], v[228:231], v[6:9]
	v_mfma_f32_16x16x32_bf16 v[2:5], v[196:199], v[228:231], v[2:5]
	v_mfma_f32_16x16x32_bf16 v[54:57], v[192:195], v[208:211], v[54:57]
	v_mfma_f32_16x16x32_bf16 v[50:53], v[200:203], v[208:211], v[50:53]
	v_mfma_f32_16x16x32_bf16 v[38:41], v[192:195], v[216:219], v[38:41]
	v_mfma_f32_16x16x32_bf16 v[34:37], v[200:203], v[216:219], v[34:37]
	v_mfma_f32_16x16x32_bf16 v[22:25], v[192:195], v[224:227], v[22:25]
	v_mfma_f32_16x16x32_bf16 v[18:21], v[200:203], v[224:227], v[18:21]
	v_mfma_f32_16x16x32_bf16 v[6:9], v[192:195], v[232:235], v[6:9]
	v_mfma_f32_16x16x32_bf16 v[2:5], v[200:203], v[232:235], v[2:5]
	s_barrier
	s_add_i32 s31, 0, 0x18000
	s_add_i32 s35, 0, 0x1c000
	v_add_u32_e32 v184, s31, v160
	v_add_u32_e32 v200, s35, v160
	ds_read_b128 v[140:143], v184
	ds_read_b128 v[144:147], v184 offset:1024
	ds_read_b128 v[180:183], v184 offset:2048
	ds_read_b128 v[184:187], v184 offset:3072
	ds_read_b128 v[188:191], v200
	ds_read_b128 v[192:195], v200 offset:1024
	ds_read_b128 v[196:199], v200 offset:2048
	ds_read_b128 v[200:203], v200 offset:3072
	s_add_u32 s10, s10, s16
	s_addc_u32 s11, s11, 0
	s_mov_b32 m0, s53
	v_lshl_add_u64 v[246:247], s[10:11], 0, v[130:131]
	ds_read_b128 v[204:207], v172 offset:32768
	ds_read_b128 v[208:211], v172 offset:33792
	ds_read_b128 v[212:215], v172 offset:34816
	ds_read_b128 v[216:219], v172 offset:35840
	ds_read_b128 v[220:223], v172 offset:36864
	ds_read_b128 v[224:227], v172 offset:37888
	ds_read_b128 v[228:231], v172 offset:38912
	ds_read_b128 v[232:235], v172 offset:39936
	global_load_lds_dwordx4 v[246:247], off
	v_lshl_add_u64 v[246:247], s[10:11], 0, v[132:133]
	s_mov_b32 m0, s54
	s_nop 0
	global_load_lds_dwordx4 v[246:247], off
	s_waitcnt vmcnt(8)
	s_waitcnt lgkmcnt(0)
	s_barrier
	s_waitcnt lgkmcnt(0)
	v_mfma_f32_16x16x32_bf16 v[126:129], v[140:143], v[204:207], v[126:129]
	v_mfma_f32_16x16x32_bf16 v[122:125], v[180:183], v[204:207], v[122:125]
	v_mfma_f32_16x16x32_bf16 v[110:113], v[140:143], v[212:215], v[110:113]
	v_mfma_f32_16x16x32_bf16 v[106:109], v[180:183], v[212:215], v[106:109]
	v_mfma_f32_16x16x32_bf16 v[94:97], v[140:143], v[220:223], v[94:97]
	v_mfma_f32_16x16x32_bf16 v[90:93], v[180:183], v[220:223], v[90:93]
	v_mfma_f32_16x16x32_bf16 v[78:81], v[140:143], v[228:231], v[78:81]
	v_mfma_f32_16x16x32_bf16 v[74:77], v[180:183], v[228:231], v[74:77]
	v_mfma_f32_16x16x32_bf16 v[126:129], v[144:147], v[208:211], v[126:129]
	v_mfma_f32_16x16x32_bf16 v[122:125], v[184:187], v[208:211], v[122:125]
	v_mfma_f32_16x16x32_bf16 v[110:113], v[144:147], v[216:219], v[110:113]
	v_mfma_f32_16x16x32_bf16 v[106:109], v[184:187], v[216:219], v[106:109]
	v_mfma_f32_16x16x32_bf16 v[94:97], v[144:147], v[224:227], v[94:97]
	v_mfma_f32_16x16x32_bf16 v[90:93], v[184:187], v[224:227], v[90:93]
	v_mfma_f32_16x16x32_bf16 v[78:81], v[144:147], v[232:235], v[78:81]
	v_mfma_f32_16x16x32_bf16 v[74:77], v[184:187], v[232:235], v[74:77]
	v_mfma_f32_16x16x32_bf16 v[118:121], v[188:191], v[204:207], v[118:121]
	v_mfma_f32_16x16x32_bf16 v[114:117], v[196:199], v[204:207], v[114:117]
	v_mfma_f32_16x16x32_bf16 v[102:105], v[188:191], v[212:215], v[102:105]
	v_mfma_f32_16x16x32_bf16 v[98:101], v[196:199], v[212:215], v[98:101]
	v_mfma_f32_16x16x32_bf16 v[86:89], v[188:191], v[220:223], v[86:89]
	v_mfma_f32_16x16x32_bf16 v[82:85], v[196:199], v[220:223], v[82:85]
	v_mfma_f32_16x16x32_bf16 v[70:73], v[188:191], v[228:231], v[70:73]
	v_mfma_f32_16x16x32_bf16 v[66:69], v[196:199], v[228:231], v[66:69]
	v_mfma_f32_16x16x32_bf16 v[118:121], v[192:195], v[208:211], v[118:121]
	v_mfma_f32_16x16x32_bf16 v[114:117], v[200:203], v[208:211], v[114:117]
	v_mfma_f32_16x16x32_bf16 v[102:105], v[192:195], v[216:219], v[102:105]
	v_mfma_f32_16x16x32_bf16 v[98:101], v[200:203], v[216:219], v[98:101]
	v_mfma_f32_16x16x32_bf16 v[86:89], v[192:195], v[224:227], v[86:89]
	v_mfma_f32_16x16x32_bf16 v[82:85], v[200:203], v[224:227], v[82:85]
	v_mfma_f32_16x16x32_bf16 v[70:73], v[192:195], v[232:235], v[70:73]
	v_mfma_f32_16x16x32_bf16 v[66:69], v[200:203], v[232:235], v[66:69]
	s_barrier
	s_add_i32 s10, s31, s20
	v_lshl_add_u64 v[148:149], v[148:149], 0, s[94:95]
	s_mov_b32 m0, s10
	ds_read_b128 v[204:207], v172 offset:49152
	ds_read_b128 v[208:211], v172 offset:50176
	ds_read_b128 v[212:215], v172 offset:51200
	ds_read_b128 v[216:219], v172 offset:52224
	ds_read_b128 v[220:223], v172 offset:53248
	ds_read_b128 v[224:227], v172 offset:54272
	ds_read_b128 v[228:231], v172 offset:55296
	ds_read_b128 v[232:235], v172 offset:56320
	global_load_lds_dwordx4 v[148:149], off
	v_lshl_add_u64 v[148:149], v[236:237], 0, s[94:95]
	s_add_i32 m0, s10, 0x2000
	s_add_i32 s10, s35, s20
	global_load_lds_dwordx4 v[148:149], off
	v_lshl_add_u64 v[148:149], v[238:239], 0, s[94:95]
	s_mov_b32 m0, s10
	s_nop 0
	global_load_lds_dwordx4 v[148:149], off
	v_lshl_add_u64 v[148:149], v[240:241], 0, s[94:95]
	s_add_i32 m0, s10, 0x2000
	s_nop 0
	global_load_lds_dwordx4 v[148:149], off
	v_lshl_add_u64 v[148:149], v[242:243], 0, s[94:95]
	s_mov_b32 m0, s56
	s_nop 0
	global_load_lds_dwordx4 v[148:149], off
	v_lshl_add_u64 v[148:149], v[244:245], 0, s[94:95]
	s_mov_b32 m0, s57
	s_nop 0
	global_load_lds_dwordx4 v[148:149], off
	s_waitcnt vmcnt(8)
	s_waitcnt lgkmcnt(0)
	s_barrier
	s_waitcnt lgkmcnt(0)
	v_mfma_f32_16x16x32_bf16 v[62:65], v[140:143], v[204:207], v[62:65]
	v_mfma_f32_16x16x32_bf16 v[58:61], v[180:183], v[204:207], v[58:61]
	v_mfma_f32_16x16x32_bf16 v[46:49], v[140:143], v[212:215], v[46:49]
	v_mfma_f32_16x16x32_bf16 v[42:45], v[180:183], v[212:215], v[42:45]
	v_mfma_f32_16x16x32_bf16 v[30:33], v[140:143], v[220:223], v[30:33]
	v_mfma_f32_16x16x32_bf16 v[26:29], v[180:183], v[220:223], v[26:29]
	v_mfma_f32_16x16x32_bf16 v[14:17], v[140:143], v[228:231], v[14:17]
	v_mfma_f32_16x16x32_bf16 v[10:13], v[180:183], v[228:231], v[10:13]
	v_mfma_f32_16x16x32_bf16 v[62:65], v[144:147], v[208:211], v[62:65]
	v_mfma_f32_16x16x32_bf16 v[58:61], v[184:187], v[208:211], v[58:61]
	v_mfma_f32_16x16x32_bf16 v[46:49], v[144:147], v[216:219], v[46:49]
	v_mfma_f32_16x16x32_bf16 v[42:45], v[184:187], v[216:219], v[42:45]
	v_mfma_f32_16x16x32_bf16 v[30:33], v[144:147], v[224:227], v[30:33]
	v_mfma_f32_16x16x32_bf16 v[26:29], v[184:187], v[224:227], v[26:29]
	v_mfma_f32_16x16x32_bf16 v[14:17], v[144:147], v[232:235], v[14:17]
	v_mfma_f32_16x16x32_bf16 v[10:13], v[184:187], v[232:235], v[10:13]
	v_mfma_f32_16x16x32_bf16 v[54:57], v[188:191], v[204:207], v[54:57]
	v_mfma_f32_16x16x32_bf16 v[50:53], v[196:199], v[204:207], v[50:53]
	v_mfma_f32_16x16x32_bf16 v[38:41], v[188:191], v[212:215], v[38:41]
	v_mfma_f32_16x16x32_bf16 v[34:37], v[196:199], v[212:215], v[34:37]
	v_mfma_f32_16x16x32_bf16 v[22:25], v[188:191], v[220:223], v[22:25]
	v_mfma_f32_16x16x32_bf16 v[18:21], v[196:199], v[220:223], v[18:21]
	v_mfma_f32_16x16x32_bf16 v[6:9], v[188:191], v[228:231], v[6:9]
	v_mfma_f32_16x16x32_bf16 v[2:5], v[196:199], v[228:231], v[2:5]
	v_mfma_f32_16x16x32_bf16 v[54:57], v[192:195], v[208:211], v[54:57]
	v_mfma_f32_16x16x32_bf16 v[50:53], v[200:203], v[208:211], v[50:53]
	v_mfma_f32_16x16x32_bf16 v[38:41], v[192:195], v[216:219], v[38:41]
	v_mfma_f32_16x16x32_bf16 v[34:37], v[200:203], v[216:219], v[34:37]
	v_mfma_f32_16x16x32_bf16 v[22:25], v[192:195], v[224:227], v[22:25]
	v_mfma_f32_16x16x32_bf16 v[18:21], v[200:203], v[224:227], v[18:21]
	v_mfma_f32_16x16x32_bf16 v[6:9], v[192:195], v[232:235], v[6:9]
	v_mfma_f32_16x16x32_bf16 v[2:5], v[200:203], v[232:235], v[2:5]
	s_barrier
	s_add_u32 s2, s2, 0x100
	s_addc_u32 s3, s3, 0
	s_add_u32 s19, s19, 0x100
	s_addc_u32 s29, s29, 0
	s_cmp_ge_u32 s30, s55
	s_mov_b32 s10, s30
	s_cbranch_scc0 .LBB0_360
	s_and_b64 vcc, exec, s[14:15]
	s_cbranch_vccz .LBB0_363
	s_barrier

.LBB0_419:
	s_add_i32 s66, s20, 2
	s_add_u32 s67, s16, 0x80
	s_addc_u32 s21, s17, 0
	s_add_i32 s72, 0, 0x10000
	s_cmp_eq_u32 s58, s20
	s_cselect_b32 s21, s1, s21
	s_cselect_b32 s20, s0, s67
	v_add_u32_e32 v140, s72, v143
	s_cselect_b32 s71, s15, s65
	s_cselect_b32 s70, s14, s64
	s_add_i32 s67, 0, 0x14000
	ds_read_b128 v[160:163], v140
	ds_read_b128 v[164:167], v140 offset:1024
	ds_read_b128 v[168:171], v140 offset:2048
	ds_read_b128 v[172:175], v140 offset:3072
	v_add_u32_e32 v140, s67, v143
	ds_read_b128 v[176:179], v140
	ds_read_b128 v[180:183], v140 offset:1024
	ds_read_b128 v[184:187], v140 offset:2048
	ds_read_b128 v[188:191], v140 offset:3072
	v_lshl_add_u64 v[140:141], s[16:17], 0, v[136:137]
	s_add_i32 m0, s35, 0xc000
	ds_read_b128 v[192:195], v146
	ds_read_b128 v[196:199], v146 offset:1024
	ds_read_b128 v[200:203], v146 offset:2048
	ds_read_b128 v[204:207], v146 offset:3072
	ds_read_b128 v[208:211], v146 offset:4096
	ds_read_b128 v[212:215], v146 offset:5120
	ds_read_b128 v[216:219], v146 offset:6144
	ds_read_b128 v[220:223], v146 offset:7168
	global_load_lds_dwordx4 v[140:141], off
	v_lshl_add_u64 v[140:141], s[16:17], 0, v[138:139]
	s_add_i32 m0, s35, 0xe000
	s_nop 0
	global_load_lds_dwordx4 v[140:141], off
	s_waitcnt vmcnt(8)
	s_waitcnt lgkmcnt(0)
	s_barrier
	s_waitcnt lgkmcnt(0)
	v_mfma_f32_16x16x32_bf16 v[126:129], v[160:163], v[192:195], v[126:129]
	v_mfma_f32_16x16x32_bf16 v[122:125], v[168:171], v[192:195], v[122:125]
	v_mfma_f32_16x16x32_bf16 v[110:113], v[160:163], v[200:203], v[110:113]
	v_mfma_f32_16x16x32_bf16 v[106:109], v[168:171], v[200:203], v[106:109]
	v_mfma_f32_16x16x32_bf16 v[94:97], v[160:163], v[208:211], v[94:97]
	v_mfma_f32_16x16x32_bf16 v[90:93], v[168:171], v[208:211], v[90:93]
	v_mfma_f32_16x16x32_bf16 v[78:81], v[160:163], v[216:219], v[78:81]
	v_mfma_f32_16x16x32_bf16 v[74:77], v[168:171], v[216:219], v[74:77]
	v_mfma_f32_16x16x32_bf16 v[126:129], v[164:167], v[196:199], v[126:129]
	v_mfma_f32_16x16x32_bf16 v[122:125], v[172:175], v[196:199], v[122:125]
	v_mfma_f32_16x16x32_bf16 v[110:113], v[164:167], v[204:207], v[110:113]
	v_mfma_f32_16x16x32_bf16 v[106:109], v[172:175], v[204:207], v[106:109]
	v_mfma_f32_16x16x32_bf16 v[94:97], v[164:167], v[212:215], v[94:97]
	v_mfma_f32_16x16x32_bf16 v[90:93], v[172:175], v[212:215], v[90:93]
	v_mfma_f32_16x16x32_bf16 v[78:81], v[164:167], v[220:223], v[78:81]
	v_mfma_f32_16x16x32_bf16 v[74:77], v[172:175], v[220:223], v[74:77]
	v_mfma_f32_16x16x32_bf16 v[118:121], v[176:179], v[192:195], v[118:121]
	v_mfma_f32_16x16x32_bf16 v[114:117], v[184:187], v[192:195], v[114:117]
	v_mfma_f32_16x16x32_bf16 v[102:105], v[176:179], v[200:203], v[102:105]
	v_mfma_f32_16x16x32_bf16 v[98:101], v[184:187], v[200:203], v[98:101]
	v_mfma_f32_16x16x32_bf16 v[86:89], v[176:179], v[208:211], v[86:89]
	v_mfma_f32_16x16x32_bf16 v[82:85], v[184:187], v[208:211], v[82:85]
	v_mfma_f32_16x16x32_bf16 v[70:73], v[176:179], v[216:219], v[70:73]
	v_mfma_f32_16x16x32_bf16 v[66:69], v[184:187], v[216:219], v[66:69]
	v_mfma_f32_16x16x32_bf16 v[118:121], v[180:183], v[196:199], v[118:121]
	v_mfma_f32_16x16x32_bf16 v[114:117], v[188:191], v[196:199], v[114:117]
	v_mfma_f32_16x16x32_bf16 v[102:105], v[180:183], v[204:207], v[102:105]
	v_mfma_f32_16x16x32_bf16 v[98:101], v[188:191], v[204:207], v[98:101]
	v_mfma_f32_16x16x32_bf16 v[86:89], v[180:183], v[212:215], v[86:89]
	v_mfma_f32_16x16x32_bf16 v[82:85], v[188:191], v[212:215], v[82:85]
	v_mfma_f32_16x16x32_bf16 v[70:73], v[180:183], v[220:223], v[70:73]
	v_mfma_f32_16x16x32_bf16 v[66:69], v[188:191], v[220:223], v[66:69]
	s_barrier
	s_add_i32 s72, s72, s30
	v_lshl_add_u64 v[140:141], s[70:71], 0, v[0:1]
	s_mov_b32 m0, s72
	ds_read_b128 v[192:195], v146 offset:16384
	ds_read_b128 v[196:199], v146 offset:17408
	ds_read_b128 v[200:203], v146 offset:18432
	ds_read_b128 v[204:207], v146 offset:19456
	ds_read_b128 v[208:211], v146 offset:20480
	ds_read_b128 v[212:215], v146 offset:21504
	ds_read_b128 v[216:219], v146 offset:22528
	ds_read_b128 v[220:223], v146 offset:23552
	global_load_lds_dwordx4 v[140:141], off
	s_add_i32 m0, s72, 0x2000
	v_lshl_add_u64 v[148:149], s[70:71], 0, v[134:135]
	s_add_u32 s70, s70, s80
	s_addc_u32 s71, s71, 0
	s_add_i32 s67, s67, s30
	global_load_lds_dwordx4 v[148:149], off
	v_lshl_add_u64 v[224:225], s[70:71], 0, v[0:1]
	s_mov_b32 m0, s67
	v_lshl_add_u64 v[226:227], s[70:71], 0, v[134:135]
	global_load_lds_dwordx4 v[224:225], off
	s_add_i32 m0, s67, 0x2000
	v_lshl_add_u64 v[228:229], s[20:21], 0, v[130:131]
	global_load_lds_dwordx4 v[226:227], off
	s_mov_b32 m0, s35
	v_lshl_add_u64 v[230:231], s[20:21], 0, v[132:133]
	global_load_lds_dwordx4 v[228:229], off
	s_mov_b32 m0, s52
	s_nop 0
	global_load_lds_dwordx4 v[230:231], off
	s_waitcnt vmcnt(8)
	s_waitcnt lgkmcnt(0)
	s_barrier
	s_waitcnt lgkmcnt(0)
	v_mfma_f32_16x16x32_bf16 v[62:65], v[160:163], v[192:195], v[62:65]
	v_mfma_f32_16x16x32_bf16 v[58:61], v[168:171], v[192:195], v[58:61]
	v_mfma_f32_16x16x32_bf16 v[46:49], v[160:163], v[200:203], v[46:49]
	v_mfma_f32_16x16x32_bf16 v[42:45], v[168:171], v[200:203], v[42:45]
	v_mfma_f32_16x16x32_bf16 v[30:33], v[160:163], v[208:211], v[30:33]
	v_mfma_f32_16x16x32_bf16 v[26:29], v[168:171], v[208:211], v[26:29]
	v_mfma_f32_16x16x32_bf16 v[14:17], v[160:163], v[216:219], v[14:17]
	v_mfma_f32_16x16x32_bf16 v[10:13], v[168:171], v[216:219], v[10:13]
	v_mfma_f32_16x16x32_bf16 v[62:65], v[164:167], v[196:199], v[62:65]
	v_mfma_f32_16x16x32_bf16 v[58:61], v[172:175], v[196:199], v[58:61]
	v_mfma_f32_16x16x32_bf16 v[46:49], v[164:167], v[204:207], v[46:49]
	v_mfma_f32_16x16x32_bf16 v[42:45], v[172:175], v[204:207], v[42:45]
	v_mfma_f32_16x16x32_bf16 v[30:33], v[164:167], v[212:215], v[30:33]
	v_mfma_f32_16x16x32_bf16 v[26:29], v[172:175], v[212:215], v[26:29]
	v_mfma_f32_16x16x32_bf16 v[14:17], v[164:167], v[220:223], v[14:17]
	v_mfma_f32_16x16x32_bf16 v[10:13], v[172:175], v[220:223], v[10:13]
	v_mfma_f32_16x16x32_bf16 v[54:57], v[176:179], v[192:195], v[54:57]
	v_mfma_f32_16x16x32_bf16 v[50:53], v[184:187], v[192:195], v[50:53]
	v_mfma_f32_16x16x32_bf16 v[38:41], v[176:179], v[200:203], v[38:41]
	v_mfma_f32_16x16x32_bf16 v[34:37], v[184:187], v[200:203], v[34:37]
	v_mfma_f32_16x16x32_bf16 v[22:25], v[176:179], v[208:211], v[22:25]
	v_mfma_f32_16x16x32_bf16 v[18:21], v[184:187], v[208:211], v[18:21]
	v_mfma_f32_16x16x32_bf16 v[6:9], v[176:179], v[216:219], v[6:9]
	v_mfma_f32_16x16x32_bf16 v[2:5], v[184:187], v[216:219], v[2:5]
	v_mfma_f32_16x16x32_bf16 v[54:57], v[180:183], v[196:199], v[54:57]
	v_mfma_f32_16x16x32_bf16 v[50:53], v[188:191], v[196:199], v[50:53]
	v_mfma_f32_16x16x32_bf16 v[38:41], v[180:183], v[204:207], v[38:41]
	v_mfma_f32_16x16x32_bf16 v[34:37], v[188:191], v[204:207], v[34:37]
	v_mfma_f32_16x16x32_bf16 v[22:25], v[180:183], v[212:215], v[22:25]
	v_mfma_f32_16x16x32_bf16 v[18:21], v[188:191], v[212:215], v[18:21]
	v_mfma_f32_16x16x32_bf16 v[6:9], v[180:183], v[220:223], v[6:9]
	v_mfma_f32_16x16x32_bf16 v[2:5], v[188:191], v[220:223], v[2:5]
	s_barrier
	s_add_i32 s67, 0, 0x18000
	v_add_u32_e32 v159, s67, v143
	s_add_i32 s70, 0, 0x1c000
	ds_read_b128 v[160:163], v159
	ds_read_b128 v[164:167], v159 offset:1024
	ds_read_b128 v[168:171], v159 offset:2048
	ds_read_b128 v[172:175], v159 offset:3072
	v_add_u32_e32 v159, s70, v143
	ds_read_b128 v[176:179], v159
	ds_read_b128 v[180:183], v159 offset:1024
	ds_read_b128 v[184:187], v159 offset:2048
	ds_read_b128 v[188:191], v159 offset:3072
	s_add_u32 s20, s20, s80
	s_addc_u32 s21, s21, 0
	s_mov_b32 m0, s53
	v_lshl_add_u64 v[232:233], s[20:21], 0, v[130:131]
	ds_read_b128 v[192:195], v146 offset:32768
	ds_read_b128 v[196:199], v146 offset:33792
	ds_read_b128 v[200:203], v146 offset:34816
	ds_read_b128 v[204:207], v146 offset:35840
	ds_read_b128 v[208:211], v146 offset:36864
	ds_read_b128 v[212:215], v146 offset:37888
	ds_read_b128 v[216:219], v146 offset:38912
	ds_read_b128 v[220:223], v146 offset:39936
	global_load_lds_dwordx4 v[232:233], off
	v_lshl_add_u64 v[232:233], s[20:21], 0, v[132:133]
	s_mov_b32 m0, s54
	s_nop 0
	global_load_lds_dwordx4 v[232:233], off
	s_waitcnt vmcnt(8)
	s_waitcnt lgkmcnt(0)
	s_barrier
	s_waitcnt lgkmcnt(0)
	v_mfma_f32_16x16x32_bf16 v[126:129], v[160:163], v[192:195], v[126:129]
	v_mfma_f32_16x16x32_bf16 v[122:125], v[168:171], v[192:195], v[122:125]
	v_mfma_f32_16x16x32_bf16 v[110:113], v[160:163], v[200:203], v[110:113]
	v_mfma_f32_16x16x32_bf16 v[106:109], v[168:171], v[200:203], v[106:109]
	v_mfma_f32_16x16x32_bf16 v[94:97], v[160:163], v[208:211], v[94:97]
	v_mfma_f32_16x16x32_bf16 v[90:93], v[168:171], v[208:211], v[90:93]
	v_mfma_f32_16x16x32_bf16 v[78:81], v[160:163], v[216:219], v[78:81]
	v_mfma_f32_16x16x32_bf16 v[74:77], v[168:171], v[216:219], v[74:77]
	v_mfma_f32_16x16x32_bf16 v[126:129], v[164:167], v[196:199], v[126:129]
	v_mfma_f32_16x16x32_bf16 v[122:125], v[172:175], v[196:199], v[122:125]
	v_mfma_f32_16x16x32_bf16 v[110:113], v[164:167], v[204:207], v[110:113]
	v_mfma_f32_16x16x32_bf16 v[106:109], v[172:175], v[204:207], v[106:109]
	v_mfma_f32_16x16x32_bf16 v[94:97], v[164:167], v[212:215], v[94:97]
	v_mfma_f32_16x16x32_bf16 v[90:93], v[172:175], v[212:215], v[90:93]
	v_mfma_f32_16x16x32_bf16 v[78:81], v[164:167], v[220:223], v[78:81]
	v_mfma_f32_16x16x32_bf16 v[74:77], v[172:175], v[220:223], v[74:77]
	v_mfma_f32_16x16x32_bf16 v[118:121], v[176:179], v[192:195], v[118:121]
	v_mfma_f32_16x16x32_bf16 v[114:117], v[184:187], v[192:195], v[114:117]
	v_mfma_f32_16x16x32_bf16 v[102:105], v[176:179], v[200:203], v[102:105]
	v_mfma_f32_16x16x32_bf16 v[98:101], v[184:187], v[200:203], v[98:101]
	v_mfma_f32_16x16x32_bf16 v[86:89], v[176:179], v[208:211], v[86:89]
	v_mfma_f32_16x16x32_bf16 v[82:85], v[184:187], v[208:211], v[82:85]
	v_mfma_f32_16x16x32_bf16 v[70:73], v[176:179], v[216:219], v[70:73]
	v_mfma_f32_16x16x32_bf16 v[66:69], v[184:187], v[216:219], v[66:69]
	v_mfma_f32_16x16x32_bf16 v[118:121], v[180:183], v[196:199], v[118:121]
	v_mfma_f32_16x16x32_bf16 v[114:117], v[188:191], v[196:199], v[114:117]
	v_mfma_f32_16x16x32_bf16 v[102:105], v[180:183], v[204:207], v[102:105]
	v_mfma_f32_16x16x32_bf16 v[98:101], v[188:191], v[204:207], v[98:101]
	v_mfma_f32_16x16x32_bf16 v[86:89], v[180:183], v[212:215], v[86:89]
	v_mfma_f32_16x16x32_bf16 v[82:85], v[188:191], v[212:215], v[82:85]
	v_mfma_f32_16x16x32_bf16 v[70:73], v[180:183], v[220:223], v[70:73]
	v_mfma_f32_16x16x32_bf16 v[66:69], v[188:191], v[220:223], v[66:69]
	s_barrier
	s_add_i32 s20, s67, s30
	v_lshl_add_u64 v[140:141], v[140:141], 0, s[94:95]
	s_mov_b32 m0, s20
	ds_read_b128 v[192:195], v146 offset:49152
	ds_read_b128 v[196:199], v146 offset:50176
	ds_read_b128 v[200:203], v146 offset:51200
	ds_read_b128 v[204:207], v146 offset:52224
	ds_read_b128 v[208:211], v146 offset:53248
	ds_read_b128 v[212:215], v146 offset:54272
	ds_read_b128 v[216:219], v146 offset:55296
	ds_read_b128 v[220:223], v146 offset:56320
	global_load_lds_dwordx4 v[140:141], off
	v_lshl_add_u64 v[140:141], v[148:149], 0, s[94:95]
	s_add_i32 m0, s20, 0x2000
	s_add_i32 s20, s70, s30
	global_load_lds_dwordx4 v[140:141], off
	v_lshl_add_u64 v[140:141], v[224:225], 0, s[94:95]
	s_mov_b32 m0, s20
	s_nop 0
	global_load_lds_dwordx4 v[140:141], off
	v_lshl_add_u64 v[140:141], v[226:227], 0, s[94:95]
	s_add_i32 m0, s20, 0x2000
	s_nop 0
	global_load_lds_dwordx4 v[140:141], off
	v_lshl_add_u64 v[140:141], v[228:229], 0, s[94:95]
	s_mov_b32 m0, s55
	s_nop 0
	global_load_lds_dwordx4 v[140:141], off
	v_lshl_add_u64 v[140:141], v[230:231], 0, s[94:95]
	s_mov_b32 m0, s56
	s_nop 0
	global_load_lds_dwordx4 v[140:141], off
	s_waitcnt vmcnt(8)
	s_waitcnt lgkmcnt(0)
	s_barrier
	s_waitcnt lgkmcnt(0)
	v_mfma_f32_16x16x32_bf16 v[62:65], v[160:163], v[192:195], v[62:65]
	v_mfma_f32_16x16x32_bf16 v[58:61], v[168:171], v[192:195], v[58:61]
	v_mfma_f32_16x16x32_bf16 v[46:49], v[160:163], v[200:203], v[46:49]
	v_mfma_f32_16x16x32_bf16 v[42:45], v[168:171], v[200:203], v[42:45]
	v_mfma_f32_16x16x32_bf16 v[30:33], v[160:163], v[208:211], v[30:33]
	v_mfma_f32_16x16x32_bf16 v[26:29], v[168:171], v[208:211], v[26:29]
	v_mfma_f32_16x16x32_bf16 v[14:17], v[160:163], v[216:219], v[14:17]
	v_mfma_f32_16x16x32_bf16 v[10:13], v[168:171], v[216:219], v[10:13]
	v_mfma_f32_16x16x32_bf16 v[62:65], v[164:167], v[196:199], v[62:65]
	v_mfma_f32_16x16x32_bf16 v[58:61], v[172:175], v[196:199], v[58:61]
	v_mfma_f32_16x16x32_bf16 v[46:49], v[164:167], v[204:207], v[46:49]
	v_mfma_f32_16x16x32_bf16 v[42:45], v[172:175], v[204:207], v[42:45]
	v_mfma_f32_16x16x32_bf16 v[30:33], v[164:167], v[212:215], v[30:33]
	v_mfma_f32_16x16x32_bf16 v[26:29], v[172:175], v[212:215], v[26:29]
	v_mfma_f32_16x16x32_bf16 v[14:17], v[164:167], v[220:223], v[14:17]
	v_mfma_f32_16x16x32_bf16 v[10:13], v[172:175], v[220:223], v[10:13]
	v_mfma_f32_16x16x32_bf16 v[54:57], v[176:179], v[192:195], v[54:57]
	v_mfma_f32_16x16x32_bf16 v[50:53], v[184:187], v[192:195], v[50:53]
	v_mfma_f32_16x16x32_bf16 v[38:41], v[176:179], v[200:203], v[38:41]
	v_mfma_f32_16x16x32_bf16 v[34:37], v[184:187], v[200:203], v[34:37]
	v_mfma_f32_16x16x32_bf16 v[22:25], v[176:179], v[208:211], v[22:25]
	v_mfma_f32_16x16x32_bf16 v[18:21], v[184:187], v[208:211], v[18:21]
	v_mfma_f32_16x16x32_bf16 v[6:9], v[176:179], v[216:219], v[6:9]
	v_mfma_f32_16x16x32_bf16 v[2:5], v[184:187], v[216:219], v[2:5]
	v_mfma_f32_16x16x32_bf16 v[54:57], v[180:183], v[196:199], v[54:57]
	v_mfma_f32_16x16x32_bf16 v[50:53], v[188:191], v[196:199], v[50:53]
	v_mfma_f32_16x16x32_bf16 v[38:41], v[180:183], v[204:207], v[38:41]
	v_mfma_f32_16x16x32_bf16 v[34:37], v[188:191], v[204:207], v[34:37]
	v_mfma_f32_16x16x32_bf16 v[22:25], v[180:183], v[212:215], v[22:25]
	v_mfma_f32_16x16x32_bf16 v[18:21], v[188:191], v[212:215], v[18:21]
	v_mfma_f32_16x16x32_bf16 v[6:9], v[180:183], v[220:223], v[6:9]
	v_mfma_f32_16x16x32_bf16 v[2:5], v[188:191], v[220:223], v[2:5]
	s_barrier
	s_add_u32 s16, s16, 0x100
	s_addc_u32 s17, s17, 0
	s_add_u32 s64, s64, 0x100
	s_addc_u32 s65, s65, 0
	s_cmp_ge_u32 s66, s57
	s_mov_b32 s20, s66
	s_cbranch_scc0 .LBB0_419
	s_and_b64 vcc, exec, s[10:11]
	s_cbranch_vccz .LBB0_422
	s_barrier
